# P12 balanced carry-in: upper 256 threads of each WG handle the mirrored chunk j^127
# speedup vs baseline: 1.0109x; 1.0031x over previous
.LBB0_1557:
	v_ashrrev_i32_e32 v6, 9, v12
	v_bfe_u32 v8, v13, 9, 1
	v_mul_u32_u24_e32 v8, 0x7f, v8
	v_xor_b32_e32 v6, v6, v8
	v_and_b32_e32 v3, 0x7f, v6
	v_bfe_u32 v14, v13, 1, 9
	v_ashrrev_i32_e32 v7, 31, v6
	v_cmp_ne_u32_e32 vcc, 0, v3
	v_mov_b32_e32 v5, 0
	v_mov_b32_e32 v4, 0
	s_and_saveexec_b64 s[38:39], vcc
	s_cbranch_execz .LBB0_1567
	v_cmp_lt_u32_e32 vcc, 7, v3
	v_mov_b32_e32 v3, v2
	v_lshlrev_b32_e32 v15, 3, v14
	v_and_b32_e32 v8, 0xffffff80, v6
	v_mov_b32_e32 v16, 0
	v_mov_b64_e32 v[4:5], v[2:3]
	s_and_saveexec_b64 s[40:41], vcc
	s_cbranch_execz .LBB0_1562
	v_ashrrev_i32_e32 v9, 31, v8
	v_lshlrev_b64 v[4:5], 12, v[8:9]
	v_lshlrev_b32_e32 v3, 1, v12
	v_or_b32_e32 v4, v4, v15
	v_and_b32_e32 v18, 0x3fe, v3
	v_lshl_add_u64 v[10:11], s[18:19], 0, v[4:5]
	v_mov_b32_e32 v4, 0
	v_and_b32_e32 v16, 0x78, v6
	s_mov_b32 s0, 0
	s_mov_b64 s[42:43], 0
	v_lshlrev_b32_e32 v3, 2, v18
	v_mov_b32_e32 v5, v4

.LBB0_1562:
	s_or_b64 exec, exec, s[40:41]
	v_and_b32_e32 v3, 7, v6
	v_cmp_ne_u32_e32 vcc, 0, v3
	s_and_saveexec_b64 s[40:41], vcc
	s_cbranch_execz .LBB0_1566
	v_add_u32_e32 v8, v16, v8
	v_ashrrev_i32_e32 v9, 31, v8
	v_lshlrev_b64 v[8:9], 12, v[8:9]
	v_or_b32_e32 v8, v8, v15
	v_lshl_add_u64 v[8:9], s[16:17], 0, v[8:9]
	s_mov_b64 s[42:43], 0
